# store coalescing (lane permute before the 16-byte stores) also for the fused final-norm write-out of P10 and the P3/P8 residual epilogue
# speedup vs baseline: 1.0083x; 1.0030x over previous
.LBB0_726:
	v_lshl_or_b32 v130, s50, 8, v191
	v_and_b32_e32 v243, 63, v204
	v_lshrrev_b32_e32 v244, 2, v243
	v_and_b32_e32 v240, 3, v243
	v_lshlrev_b32_e32 v242, 4, v240
	v_add_u32_e32 v242, v242, v244
	v_lshlrev_b32_e32 v242, 2, v242
	v_and_b32_e32 v241, 15, v243
	v_sub_u32_e32 v244, v244, v241
	v_lshlrev_b32_e32 v244, 11, v244
	v_bfe_u32 v241, v243, 4, 2
	v_sub_u32_e32 v240, v240, v241
	v_lshlrev_b32_e32 v240, 4, v240
	v_add_u32_e32 v240, v244, v240
	v_ashrrev_i32_e32 v241, 31, v240
	v_lshl_add_u32 v168, s51, 8, v176
	v_ashrrev_i32_e32 v131, 31, v130
	v_lshlrev_b64 v[170:171], 1, v[130:131]
	v_or_b32_e32 v130, 16, v168
	v_ashrrev_i32_e32 v131, 31, v130
	v_lshlrev_b64 v[130:131], 11, v[130:131]
	v_lshl_add_u64 v[130:131], s[64:65], 0, v[130:131]
	v_lshl_add_u64 v[186:187], v[130:131], 0, v[170:171]
	v_or_b32_e32 v130, 32, v168
	v_ashrrev_i32_e32 v131, 31, v130
	v_lshlrev_b64 v[130:131], 11, v[130:131]
	v_lshl_add_u64 v[130:131], s[64:65], 0, v[130:131]
	v_lshl_add_u64 v[174:175], v[130:131], 0, v[170:171]
	v_or_b32_e32 v130, 48, v168
	v_ashrrev_i32_e32 v169, 31, v168
	v_ashrrev_i32_e32 v131, 31, v130
	v_lshlrev_b64 v[132:133], 11, v[168:169]
	v_lshlrev_b64 v[130:131], 11, v[130:131]
	v_lshl_add_u64 v[132:133], s[64:65], 0, v[132:133]
	v_lshl_add_u64 v[130:131], s[64:65], 0, v[130:131]
	v_lshl_add_u64 v[188:189], v[132:133], 0, v[170:171]
	v_lshl_add_u64 v[172:173], v[130:131], 0, v[170:171]
	global_load_dwordx4 v[194:197], v[188:189], off
	global_load_dwordx4 v[154:157], v[188:189], off offset:256
	global_load_dwordx4 v[150:153], v[186:187], off
	global_load_dwordx4 v[146:149], v[186:187], off offset:256
	global_load_dwordx4 v[142:145], v[174:175], off
	global_load_dwordx4 v[138:141], v[174:175], off offset:256
	global_load_dwordx4 v[134:137], v[172:173], off
	global_load_dwordx4 v[130:133], v[172:173], off offset:256
	s_waitcnt vmcnt(0)
	v_lshlrev_b32_e32 v198, 16, v194
	v_and_b32_e32 v199, 0xffff0000, v194
	v_lshlrev_b32_e32 v194, 16, v195
	v_and_b32_e32 v195, 0xffff0000, v195
	v_pk_add_f32 v[128:129], v[128:129], v[194:195]
	v_lshlrev_b32_e32 v194, 16, v196
	v_and_b32_e32 v195, 0xffff0000, v196
	v_lshlrev_b32_e32 v196, 16, v197
	v_and_b32_e32 v197, 0xffff0000, v197
	v_cndmask_b32_e64 v193, 0, 1, s[94:95]
	v_pk_add_f32 v[126:127], v[126:127], v[198:199]
	v_pk_add_f32 v[124:125], v[124:125], v[196:197]
	v_cmp_ne_u32_e64 s[42:43], 1, v193
	s_andn2_b64 vcc, exec, s[94:95]
	v_pk_add_f32 v[122:123], v[122:123], v[194:195]
	s_cbranch_vccnz .LBB0_728
	v_cvt_pk_bf16_f32 v194, v126, v127
	v_cvt_pk_bf16_f32 v195, v128, v129
	v_cvt_pk_bf16_f32 v196, v122, v123
	v_cvt_pk_bf16_f32 v197, v124, v125
	v_lshl_add_u64 v[188:189], v[188:189], 0, v[240:241]
	ds_bpermute_b32 v194, v242, v194
	ds_bpermute_b32 v195, v242, v195
	ds_bpermute_b32 v196, v242, v196
	ds_bpermute_b32 v197, v242, v197
	s_waitcnt lgkmcnt(0)
	global_store_dwordx4 v[188:189], v[194:197], off
.LBB0_728:
	s_nop 1
	v_lshlrev_b32_e32 v194, 16, v154
	v_and_b32_e32 v195, 0xffff0000, v154
	v_lshlrev_b32_e32 v154, 16, v155
	v_and_b32_e32 v155, 0xffff0000, v155
	v_pk_add_f32 v[120:121], v[120:121], v[154:155]
	v_lshlrev_b32_e32 v154, 16, v156
	v_and_b32_e32 v155, 0xffff0000, v156
	v_lshlrev_b32_e32 v156, 16, v157
	v_and_b32_e32 v157, 0xffff0000, v157
	v_pk_add_f32 v[118:119], v[118:119], v[194:195]
	v_pk_add_f32 v[116:117], v[116:117], v[156:157]
	s_and_b64 vcc, exec, s[42:43]
	v_pk_add_f32 v[114:115], v[114:115], v[154:155]
	s_cbranch_vccnz .LBB0_730
	v_cvt_pk_bf16_f32 v154, v118, v119
	v_cvt_pk_bf16_f32 v155, v120, v121
	v_cvt_pk_bf16_f32 v156, v114, v115
	v_cvt_pk_bf16_f32 v157, v116, v117
	ds_bpermute_b32 v154, v242, v154
	ds_bpermute_b32 v155, v242, v155
	ds_bpermute_b32 v156, v242, v156
	ds_bpermute_b32 v157, v242, v157
	s_waitcnt lgkmcnt(0)
	global_store_dwordx4 v[188:189], v[154:157], off offset:256
.LBB0_730:
	v_mul_f32_e32 v127, v127, v127
	v_mul_f32_e32 v123, v123, v123
	v_mul_f32_e32 v119, v119, v119
	v_mul_f32_e32 v115, v115, v115
	v_fmac_f32_e32 v127, v126, v126
	v_mul_f32_e32 v126, v129, v129
	v_fmac_f32_e32 v123, v122, v122
	v_mul_f32_e32 v122, v125, v125
	v_fmac_f32_e32 v119, v118, v118
	v_mul_f32_e32 v118, v121, v121
	v_fmac_f32_e32 v115, v114, v114
	v_mul_f32_e32 v114, v117, v117
	v_fmac_f32_e32 v126, v128, v128
	v_fmac_f32_e32 v122, v124, v124
	v_fmac_f32_e32 v118, v120, v120
	v_fmac_f32_e32 v114, v116, v116
	v_add_f32_e32 v126, v127, v126
	v_add_f32_e32 v122, v123, v122
	v_cmp_lt_i32_e32 vcc, v210, v206
	v_add_f32_e32 v118, v119, v118
	v_add_f32_e32 v114, v115, v114
	v_add_f32_e32 v123, v126, v122
	v_cndmask_b32_e32 v122, v205, v210, vcc
	v_add_f32_e32 v114, v118, v114
	v_lshlrev_b32_e32 v122, 2, v122
	v_add_f32_e32 v114, v123, v114
	ds_bpermute_b32 v115, v122, v114
	v_cmp_lt_i32_e32 vcc, v209, v206
	v_lshlrev_b32_e32 v118, 16, v150
	v_and_b32_e32 v119, 0xffff0000, v150
	v_cndmask_b32_e32 v116, v205, v209, vcc
	v_lshlrev_b32_e32 v116, 2, v116
	s_waitcnt lgkmcnt(0)
	v_add_f32_e32 v114, v114, v115
	ds_bpermute_b32 v115, v116, v114
	v_lshlrev_b32_e32 v120, 16, v151
	v_and_b32_e32 v121, 0xffff0000, v151
	v_pk_add_f32 v[112:113], v[112:113], v[120:121]
	v_pk_add_f32 v[110:111], v[110:111], v[118:119]
	v_lshlrev_b32_e32 v118, 16, v152
	v_and_b32_e32 v119, 0xffff0000, v152
	v_lshlrev_b32_e32 v120, 16, v153
	v_and_b32_e32 v121, 0xffff0000, v153
	v_pk_add_f32 v[108:109], v[108:109], v[120:121]
	s_and_b64 vcc, exec, s[42:43]
	v_pk_add_f32 v[106:107], v[106:107], v[118:119]
	s_cbranch_vccnz .LBB0_732
	v_cvt_pk_bf16_f32 v118, v110, v111
	v_cvt_pk_bf16_f32 v119, v112, v113
	v_cvt_pk_bf16_f32 v120, v106, v107
	v_cvt_pk_bf16_f32 v121, v108, v109
	v_lshl_add_u64 v[186:187], v[186:187], 0, v[240:241]
	ds_bpermute_b32 v118, v242, v118
	ds_bpermute_b32 v119, v242, v119
	ds_bpermute_b32 v120, v242, v120
	ds_bpermute_b32 v121, v242, v121
	s_waitcnt lgkmcnt(0)
	global_store_dwordx4 v[186:187], v[118:121], off
.LBB0_732:
	s_nop 1
	v_lshlrev_b32_e32 v118, 16, v146
	v_and_b32_e32 v119, 0xffff0000, v146
	v_lshlrev_b32_e32 v120, 16, v147
	v_and_b32_e32 v121, 0xffff0000, v147
	v_pk_add_f32 v[104:105], v[104:105], v[120:121]
	v_pk_add_f32 v[102:103], v[102:103], v[118:119]
	v_lshlrev_b32_e32 v118, 16, v148
	v_and_b32_e32 v119, 0xffff0000, v148
	v_lshlrev_b32_e32 v120, 16, v149
	v_and_b32_e32 v121, 0xffff0000, v149
	v_pk_add_f32 v[100:101], v[100:101], v[120:121]
	s_and_b64 vcc, exec, s[42:43]
	v_pk_add_f32 v[98:99], v[98:99], v[118:119]
	s_cbranch_vccnz .LBB0_734
	v_cvt_pk_bf16_f32 v118, v102, v103
	v_cvt_pk_bf16_f32 v119, v104, v105
	v_cvt_pk_bf16_f32 v120, v98, v99
	v_cvt_pk_bf16_f32 v121, v100, v101
	ds_bpermute_b32 v118, v242, v118
	ds_bpermute_b32 v119, v242, v119
	ds_bpermute_b32 v120, v242, v120
	ds_bpermute_b32 v121, v242, v121
	s_waitcnt lgkmcnt(0)
	global_store_dwordx4 v[186:187], v[118:121], off offset:256
.LBB0_734:
	v_mul_f32_e32 v111, v111, v111
	v_mul_f32_e32 v107, v107, v107
	v_mul_f32_e32 v103, v103, v103
	v_mul_f32_e32 v99, v99, v99
	v_fmac_f32_e32 v111, v110, v110
	v_mul_f32_e32 v110, v113, v113
	v_fmac_f32_e32 v107, v106, v106
	v_mul_f32_e32 v106, v109, v109
	v_fmac_f32_e32 v103, v102, v102
	v_mul_f32_e32 v102, v105, v105
	v_fmac_f32_e32 v99, v98, v98
	v_mul_f32_e32 v98, v101, v101
	v_fmac_f32_e32 v110, v112, v112
	v_fmac_f32_e32 v106, v108, v108
	v_fmac_f32_e32 v102, v104, v104
	v_fmac_f32_e32 v98, v100, v100
	v_add_f32_e32 v110, v111, v110
	v_add_f32_e32 v106, v107, v106
	v_add_f32_e32 v102, v103, v102
	v_add_f32_e32 v98, v99, v98
	v_add_f32_e32 v106, v110, v106
	v_add_f32_e32 v98, v102, v98
	v_add_f32_e32 v98, v106, v98
	ds_bpermute_b32 v99, v122, v98
	v_lshlrev_b32_e32 v100, 16, v143
	v_and_b32_e32 v101, 0xffff0000, v143
	v_pk_add_f32 v[96:97], v[96:97], v[100:101]
	v_lshlrev_b32_e32 v100, 16, v145
	s_waitcnt lgkmcnt(0)
	v_add_f32_e32 v102, v98, v99
	ds_bpermute_b32 v103, v116, v102
	v_lshlrev_b32_e32 v98, 16, v142
	v_and_b32_e32 v99, 0xffff0000, v142
	v_pk_add_f32 v[94:95], v[94:95], v[98:99]
	v_lshlrev_b32_e32 v98, 16, v144
	v_and_b32_e32 v99, 0xffff0000, v144
	v_and_b32_e32 v101, 0xffff0000, v145
	v_pk_add_f32 v[92:93], v[92:93], v[100:101]
	s_and_b64 vcc, exec, s[42:43]
	v_pk_add_f32 v[90:91], v[90:91], v[98:99]
	s_cbranch_vccnz .LBB0_736
	v_cvt_pk_bf16_f32 v98, v94, v95
	v_cvt_pk_bf16_f32 v99, v96, v97
	v_cvt_pk_bf16_f32 v100, v90, v91
	v_cvt_pk_bf16_f32 v101, v92, v93
	v_lshl_add_u64 v[174:175], v[174:175], 0, v[240:241]
	ds_bpermute_b32 v98, v242, v98
	ds_bpermute_b32 v99, v242, v99
	ds_bpermute_b32 v100, v242, v100
	ds_bpermute_b32 v101, v242, v101
	s_waitcnt lgkmcnt(0)
	global_store_dwordx4 v[174:175], v[98:101], off
.LBB0_736:
	s_nop 1
	v_lshlrev_b32_e32 v98, 16, v138
	v_and_b32_e32 v99, 0xffff0000, v138
	v_lshlrev_b32_e32 v100, 16, v139
	v_and_b32_e32 v101, 0xffff0000, v139
	v_pk_add_f32 v[88:89], v[88:89], v[100:101]
	v_pk_add_f32 v[86:87], v[86:87], v[98:99]
	v_lshlrev_b32_e32 v98, 16, v140
	v_and_b32_e32 v99, 0xffff0000, v140
	v_lshlrev_b32_e32 v100, 16, v141
	v_and_b32_e32 v101, 0xffff0000, v141
	v_pk_add_f32 v[84:85], v[84:85], v[100:101]
	s_and_b64 vcc, exec, s[42:43]
	v_pk_add_f32 v[82:83], v[82:83], v[98:99]
	s_cbranch_vccnz .LBB0_738
	v_cvt_pk_bf16_f32 v98, v86, v87
	v_cvt_pk_bf16_f32 v99, v88, v89
	v_cvt_pk_bf16_f32 v100, v82, v83
	v_cvt_pk_bf16_f32 v101, v84, v85
	ds_bpermute_b32 v98, v242, v98
	ds_bpermute_b32 v99, v242, v99
	ds_bpermute_b32 v100, v242, v100
	ds_bpermute_b32 v101, v242, v101
	s_waitcnt lgkmcnt(0)
	global_store_dwordx4 v[174:175], v[98:101], off offset:256
.LBB0_738:
	v_mul_f32_e32 v95, v95, v95
	v_mul_f32_e32 v91, v91, v91
	v_mul_f32_e32 v87, v87, v87
	v_mul_f32_e32 v83, v83, v83
	v_fmac_f32_e32 v95, v94, v94
	v_mul_f32_e32 v94, v97, v97
	v_fmac_f32_e32 v91, v90, v90
	v_mul_f32_e32 v90, v93, v93
	v_fmac_f32_e32 v87, v86, v86
	v_mul_f32_e32 v86, v89, v89
	v_fmac_f32_e32 v83, v82, v82
	v_mul_f32_e32 v82, v85, v85
	v_fmac_f32_e32 v94, v96, v96
	v_fmac_f32_e32 v90, v92, v92
	v_fmac_f32_e32 v86, v88, v88
	v_fmac_f32_e32 v82, v84, v84
	v_add_f32_e32 v94, v95, v94
	v_add_f32_e32 v90, v91, v90
	v_add_f32_e32 v86, v87, v86
	v_add_f32_e32 v82, v83, v82
	v_add_f32_e32 v90, v94, v90
	v_add_f32_e32 v82, v86, v82
	v_add_f32_e32 v82, v90, v82
	ds_bpermute_b32 v83, v122, v82
	v_lshlrev_b32_e32 v84, 16, v135
	v_and_b32_e32 v85, 0xffff0000, v135
	v_pk_add_f32 v[80:81], v[80:81], v[84:85]
	v_lshlrev_b32_e32 v84, 16, v137
	s_waitcnt lgkmcnt(0)
	v_add_f32_e32 v104, v82, v83
	ds_bpermute_b32 v105, v116, v104
	v_lshlrev_b32_e32 v82, 16, v134
	v_and_b32_e32 v83, 0xffff0000, v134
	v_pk_add_f32 v[78:79], v[78:79], v[82:83]
	v_lshlrev_b32_e32 v82, 16, v136
	v_and_b32_e32 v83, 0xffff0000, v136
	v_and_b32_e32 v85, 0xffff0000, v137
	v_pk_add_f32 v[76:77], v[76:77], v[84:85]
	s_and_b64 vcc, exec, s[42:43]
	v_pk_add_f32 v[74:75], v[74:75], v[82:83]
	s_cbranch_vccnz .LBB0_740
	v_cvt_pk_bf16_f32 v82, v78, v79
	v_cvt_pk_bf16_f32 v83, v80, v81
	v_cvt_pk_bf16_f32 v84, v74, v75
	v_cvt_pk_bf16_f32 v85, v76, v77
	v_lshl_add_u64 v[172:173], v[172:173], 0, v[240:241]
	ds_bpermute_b32 v82, v242, v82
	ds_bpermute_b32 v83, v242, v83
	ds_bpermute_b32 v84, v242, v84
	ds_bpermute_b32 v85, v242, v85
	s_waitcnt lgkmcnt(0)
	global_store_dwordx4 v[172:173], v[82:85], off
.LBB0_740:
	s_nop 1
	v_lshlrev_b32_e32 v82, 16, v130
	v_and_b32_e32 v83, 0xffff0000, v130
	v_lshlrev_b32_e32 v84, 16, v131
	v_and_b32_e32 v85, 0xffff0000, v131
	v_pk_add_f32 v[72:73], v[72:73], v[84:85]
	v_pk_add_f32 v[70:71], v[70:71], v[82:83]
	v_lshlrev_b32_e32 v82, 16, v132
	v_and_b32_e32 v83, 0xffff0000, v132
	v_lshlrev_b32_e32 v84, 16, v133
	v_and_b32_e32 v85, 0xffff0000, v133
	v_pk_add_f32 v[68:69], v[68:69], v[84:85]
	s_and_b64 vcc, exec, s[42:43]
	v_pk_add_f32 v[66:67], v[66:67], v[82:83]
	s_cbranch_vccnz .LBB0_742
	v_cvt_pk_bf16_f32 v82, v70, v71
	v_cvt_pk_bf16_f32 v83, v72, v73
	v_cvt_pk_bf16_f32 v84, v66, v67
	v_cvt_pk_bf16_f32 v85, v68, v69
	ds_bpermute_b32 v82, v242, v82
	ds_bpermute_b32 v83, v242, v83
	ds_bpermute_b32 v84, v242, v84
	ds_bpermute_b32 v85, v242, v85
	s_waitcnt lgkmcnt(0)
	global_store_dwordx4 v[172:173], v[82:85], off offset:256
.LBB0_742:
	v_mul_f32_e32 v79, v79, v79
	v_mul_f32_e32 v75, v75, v75
	v_mul_f32_e32 v71, v71, v71
	v_mul_f32_e32 v67, v67, v67
	v_fmac_f32_e32 v79, v78, v78
	v_mul_f32_e32 v78, v81, v81
	v_fmac_f32_e32 v75, v74, v74
	v_mul_f32_e32 v74, v77, v77
	v_fmac_f32_e32 v71, v70, v70
	v_mul_f32_e32 v70, v73, v73
	v_fmac_f32_e32 v67, v66, v66
	v_mul_f32_e32 v66, v69, v69
	v_fmac_f32_e32 v78, v80, v80
	v_fmac_f32_e32 v74, v76, v76
	v_fmac_f32_e32 v70, v72, v72
	v_fmac_f32_e32 v66, v68, v68
	v_add_f32_e32 v78, v79, v78
	v_add_f32_e32 v74, v75, v74
	v_add_f32_e32 v70, v71, v70
	v_add_f32_e32 v66, v67, v66
	v_add_f32_e32 v74, v78, v74
	v_add_f32_e32 v66, v70, v66
	v_add_f32_e32 v66, v74, v66
	ds_bpermute_b32 v67, v122, v66
	s_waitcnt lgkmcnt(0)
	v_add_f32_e32 v106, v66, v67
	v_add_u32_e32 v66, 0x80, v168
	v_ashrrev_i32_e32 v67, 31, v66
	v_lshlrev_b64 v[66:67], 11, v[66:67]
	v_lshl_add_u64 v[66:67], s[64:65], 0, v[66:67]
	v_lshl_add_u64 v[100:101], v[66:67], 0, v[170:171]
	v_add_u32_e32 v66, 0x90, v168
	v_ashrrev_i32_e32 v67, 31, v66
	v_lshlrev_b64 v[66:67], 11, v[66:67]
	v_lshl_add_u64 v[66:67], s[64:65], 0, v[66:67]
	v_lshl_add_u64 v[98:99], v[66:67], 0, v[170:171]
	v_add_u32_e32 v66, 0xa0, v168
	v_ashrrev_i32_e32 v67, 31, v66
	v_lshlrev_b64 v[66:67], 11, v[66:67]
	v_lshl_add_u64 v[66:67], s[64:65], 0, v[66:67]
	v_lshl_add_u64 v[96:97], v[66:67], 0, v[170:171]
	v_add_u32_e32 v66, 0xb0, v168
	v_ashrrev_i32_e32 v67, 31, v66
	v_lshlrev_b64 v[66:67], 11, v[66:67]
	v_lshl_add_u64 v[66:67], s[64:65], 0, v[66:67]
	v_lshl_add_u64 v[94:95], v[66:67], 0, v[170:171]
	global_load_dwordx4 v[108:111], v[100:101], off
	global_load_dwordx4 v[90:93], v[100:101], off offset:256
	global_load_dwordx4 v[86:89], v[98:99], off
	global_load_dwordx4 v[82:85], v[98:99], off offset:256
	global_load_dwordx4 v[78:81], v[96:97], off
	global_load_dwordx4 v[74:77], v[96:97], off offset:256
	global_load_dwordx4 v[70:73], v[94:95], off
	global_load_dwordx4 v[66:69], v[94:95], off offset:256
	ds_bpermute_b32 v107, v116, v106
	s_waitcnt vmcnt(7)
	v_lshlrev_b32_e32 v112, 16, v108
	v_and_b32_e32 v113, 0xffff0000, v108
	v_lshlrev_b32_e32 v108, 16, v109
	v_and_b32_e32 v109, 0xffff0000, v109
	v_pk_add_f32 v[64:65], v[64:65], v[108:109]
	v_lshlrev_b32_e32 v108, 16, v110
	v_and_b32_e32 v109, 0xffff0000, v110
	v_lshlrev_b32_e32 v110, 16, v111
	v_and_b32_e32 v111, 0xffff0000, v111
	v_pk_add_f32 v[62:63], v[62:63], v[112:113]
	v_pk_add_f32 v[60:61], v[60:61], v[110:111]
	s_and_b64 vcc, exec, s[42:43]
	v_pk_add_f32 v[58:59], v[58:59], v[108:109]
	s_cbranch_vccnz .LBB0_744
	v_cvt_pk_bf16_f32 v108, v62, v63
	v_cvt_pk_bf16_f32 v109, v64, v65
	v_cvt_pk_bf16_f32 v110, v58, v59
	v_cvt_pk_bf16_f32 v111, v60, v61
	v_lshl_add_u64 v[100:101], v[100:101], 0, v[240:241]
	ds_bpermute_b32 v108, v242, v108
	ds_bpermute_b32 v109, v242, v109
	ds_bpermute_b32 v110, v242, v110
	ds_bpermute_b32 v111, v242, v111
	s_waitcnt lgkmcnt(0)
	global_store_dwordx4 v[100:101], v[108:111], off
.LBB0_744:
	s_waitcnt vmcnt(6)
	s_nop 0
	v_lshlrev_b32_e32 v108, 16, v90
	v_and_b32_e32 v109, 0xffff0000, v90
	v_lshlrev_b32_e32 v90, 16, v91
	v_and_b32_e32 v91, 0xffff0000, v91
	v_pk_add_f32 v[56:57], v[56:57], v[90:91]
	v_lshlrev_b32_e32 v90, 16, v92
	v_and_b32_e32 v91, 0xffff0000, v92
	v_lshlrev_b32_e32 v92, 16, v93
	v_and_b32_e32 v93, 0xffff0000, v93
	v_pk_add_f32 v[54:55], v[54:55], v[108:109]
	v_pk_add_f32 v[52:53], v[52:53], v[92:93]
	s_and_b64 vcc, exec, s[42:43]
	v_pk_add_f32 v[50:51], v[50:51], v[90:91]
	s_cbranch_vccnz .LBB0_746
	v_cvt_pk_bf16_f32 v90, v54, v55
	v_cvt_pk_bf16_f32 v91, v56, v57
	v_cvt_pk_bf16_f32 v92, v50, v51
	v_cvt_pk_bf16_f32 v93, v52, v53
	ds_bpermute_b32 v90, v242, v90
	ds_bpermute_b32 v91, v242, v91
	ds_bpermute_b32 v92, v242, v92
	ds_bpermute_b32 v93, v242, v93
	s_waitcnt lgkmcnt(0)
	global_store_dwordx4 v[100:101], v[90:93], off offset:256
.LBB0_746:
	v_mul_f32_e32 v63, v63, v63
	v_mul_f32_e32 v59, v59, v59
	v_mul_f32_e32 v55, v55, v55
	v_mul_f32_e32 v51, v51, v51
	v_fmac_f32_e32 v63, v62, v62
	v_mul_f32_e32 v62, v65, v65
	v_fmac_f32_e32 v59, v58, v58
	v_mul_f32_e32 v58, v61, v61
	v_fmac_f32_e32 v55, v54, v54
	v_mul_f32_e32 v54, v57, v57
	v_fmac_f32_e32 v51, v50, v50
	v_mul_f32_e32 v50, v53, v53
	v_fmac_f32_e32 v62, v64, v64
	v_fmac_f32_e32 v58, v60, v60
	v_fmac_f32_e32 v54, v56, v56
	v_fmac_f32_e32 v50, v52, v52
	v_add_f32_e32 v62, v63, v62
	v_add_f32_e32 v58, v59, v58
	v_add_f32_e32 v54, v55, v54
	v_add_f32_e32 v50, v51, v50
	v_add_f32_e32 v58, v62, v58
	v_add_f32_e32 v50, v54, v50
	v_add_f32_e32 v50, v58, v50
	ds_bpermute_b32 v51, v122, v50
	s_waitcnt vmcnt(5)
	v_lshlrev_b32_e32 v52, 16, v86
	v_and_b32_e32 v53, 0xffff0000, v86
	v_lshlrev_b32_e32 v54, 16, v87
	v_and_b32_e32 v55, 0xffff0000, v87
	s_waitcnt lgkmcnt(0)
	v_add_f32_e32 v50, v50, v51
	ds_bpermute_b32 v51, v116, v50
	v_pk_add_f32 v[48:49], v[48:49], v[54:55]
	v_pk_add_f32 v[46:47], v[46:47], v[52:53]
	v_lshlrev_b32_e32 v52, 16, v88
	v_and_b32_e32 v53, 0xffff0000, v88
	v_lshlrev_b32_e32 v54, 16, v89
	v_and_b32_e32 v55, 0xffff0000, v89
	v_pk_add_f32 v[44:45], v[44:45], v[54:55]
	s_and_b64 vcc, exec, s[42:43]
	v_pk_add_f32 v[42:43], v[42:43], v[52:53]
	s_cbranch_vccnz .LBB0_748
	v_cvt_pk_bf16_f32 v52, v46, v47
	v_cvt_pk_bf16_f32 v53, v48, v49
	v_cvt_pk_bf16_f32 v54, v42, v43
	v_cvt_pk_bf16_f32 v55, v44, v45
	v_lshl_add_u64 v[98:99], v[98:99], 0, v[240:241]
	ds_bpermute_b32 v52, v242, v52
	ds_bpermute_b32 v53, v242, v53
	ds_bpermute_b32 v54, v242, v54
	ds_bpermute_b32 v55, v242, v55
	s_waitcnt lgkmcnt(0)
	global_store_dwordx4 v[98:99], v[52:55], off
.LBB0_748:
	s_waitcnt vmcnt(4)
	s_nop 0
	v_lshlrev_b32_e32 v52, 16, v82
	v_and_b32_e32 v53, 0xffff0000, v82
	v_lshlrev_b32_e32 v54, 16, v83
	v_and_b32_e32 v55, 0xffff0000, v83
	v_pk_add_f32 v[40:41], v[40:41], v[54:55]
	v_pk_add_f32 v[38:39], v[38:39], v[52:53]
	v_lshlrev_b32_e32 v52, 16, v84
	v_and_b32_e32 v53, 0xffff0000, v84
	v_lshlrev_b32_e32 v54, 16, v85
	v_and_b32_e32 v55, 0xffff0000, v85
	v_pk_add_f32 v[36:37], v[36:37], v[54:55]
	s_and_b64 vcc, exec, s[42:43]
	v_pk_add_f32 v[34:35], v[34:35], v[52:53]
	s_cbranch_vccnz .LBB0_750
	v_cvt_pk_bf16_f32 v52, v38, v39
	v_cvt_pk_bf16_f32 v53, v40, v41
	v_cvt_pk_bf16_f32 v54, v34, v35
	v_cvt_pk_bf16_f32 v55, v36, v37
	ds_bpermute_b32 v52, v242, v52
	ds_bpermute_b32 v53, v242, v53
	ds_bpermute_b32 v54, v242, v54
	ds_bpermute_b32 v55, v242, v55
	s_waitcnt lgkmcnt(0)
	global_store_dwordx4 v[98:99], v[52:55], off offset:256
.LBB0_750:
	v_mul_f32_e32 v47, v47, v47
	v_mul_f32_e32 v43, v43, v43
	v_mul_f32_e32 v39, v39, v39
	v_mul_f32_e32 v35, v35, v35
	v_fmac_f32_e32 v47, v46, v46
	v_mul_f32_e32 v46, v49, v49
	v_fmac_f32_e32 v43, v42, v42
	v_mul_f32_e32 v42, v45, v45
	v_fmac_f32_e32 v39, v38, v38
	v_mul_f32_e32 v38, v41, v41
	v_fmac_f32_e32 v35, v34, v34
	v_mul_f32_e32 v34, v37, v37
	v_fmac_f32_e32 v46, v48, v48
	v_fmac_f32_e32 v42, v44, v44
	v_fmac_f32_e32 v38, v40, v40
	v_fmac_f32_e32 v34, v36, v36
	v_add_f32_e32 v46, v47, v46
	v_add_f32_e32 v42, v43, v42
	v_add_f32_e32 v38, v39, v38
	v_add_f32_e32 v34, v35, v34
	v_add_f32_e32 v42, v46, v42
	v_add_f32_e32 v34, v38, v34
	v_add_f32_e32 v34, v42, v34
	ds_bpermute_b32 v35, v122, v34
	s_waitcnt vmcnt(3)
	v_lshlrev_b32_e32 v36, 16, v78
	v_and_b32_e32 v37, 0xffff0000, v78
	v_lshlrev_b32_e32 v38, 16, v79
	v_and_b32_e32 v39, 0xffff0000, v79
	s_waitcnt lgkmcnt(0)
	v_add_f32_e32 v34, v34, v35
	ds_bpermute_b32 v35, v116, v34
	v_pk_add_f32 v[32:33], v[32:33], v[38:39]
	v_pk_add_f32 v[30:31], v[30:31], v[36:37]
	v_lshlrev_b32_e32 v36, 16, v80
	v_and_b32_e32 v37, 0xffff0000, v80
	v_lshlrev_b32_e32 v38, 16, v81
	v_and_b32_e32 v39, 0xffff0000, v81
	v_pk_add_f32 v[28:29], v[28:29], v[38:39]
	s_and_b64 vcc, exec, s[42:43]
	v_pk_add_f32 v[26:27], v[26:27], v[36:37]
	s_cbranch_vccnz .LBB0_752
	v_cvt_pk_bf16_f32 v36, v30, v31
	v_cvt_pk_bf16_f32 v37, v32, v33
	v_cvt_pk_bf16_f32 v38, v26, v27
	v_cvt_pk_bf16_f32 v39, v28, v29
	v_lshl_add_u64 v[96:97], v[96:97], 0, v[240:241]
	ds_bpermute_b32 v36, v242, v36
	ds_bpermute_b32 v37, v242, v37
	ds_bpermute_b32 v38, v242, v38
	ds_bpermute_b32 v39, v242, v39
	s_waitcnt lgkmcnt(0)
	global_store_dwordx4 v[96:97], v[36:39], off
.LBB0_752:
	s_waitcnt vmcnt(2)
	s_nop 0
	v_lshlrev_b32_e32 v36, 16, v74
	v_and_b32_e32 v37, 0xffff0000, v74
	v_lshlrev_b32_e32 v38, 16, v75
	v_and_b32_e32 v39, 0xffff0000, v75
	v_pk_add_f32 v[24:25], v[24:25], v[38:39]
	v_pk_add_f32 v[22:23], v[22:23], v[36:37]
	v_lshlrev_b32_e32 v36, 16, v76
	v_and_b32_e32 v37, 0xffff0000, v76
	v_lshlrev_b32_e32 v38, 16, v77
	v_and_b32_e32 v39, 0xffff0000, v77
	v_pk_add_f32 v[20:21], v[20:21], v[38:39]
	s_and_b64 vcc, exec, s[42:43]
	v_pk_add_f32 v[18:19], v[18:19], v[36:37]
	s_cbranch_vccnz .LBB0_754
	v_cvt_pk_bf16_f32 v36, v22, v23
	v_cvt_pk_bf16_f32 v37, v24, v25
	v_cvt_pk_bf16_f32 v38, v18, v19
	v_cvt_pk_bf16_f32 v39, v20, v21
	ds_bpermute_b32 v36, v242, v36
	ds_bpermute_b32 v37, v242, v37
	ds_bpermute_b32 v38, v242, v38
	ds_bpermute_b32 v39, v242, v39
	s_waitcnt lgkmcnt(0)
	global_store_dwordx4 v[96:97], v[36:39], off offset:256
.LBB0_754:
	v_mul_f32_e32 v31, v31, v31
	v_mul_f32_e32 v27, v27, v27
	v_mul_f32_e32 v23, v23, v23
	v_mul_f32_e32 v19, v19, v19
	v_fmac_f32_e32 v31, v30, v30
	v_mul_f32_e32 v30, v33, v33
	v_fmac_f32_e32 v27, v26, v26
	v_mul_f32_e32 v26, v29, v29
	v_fmac_f32_e32 v23, v22, v22
	v_mul_f32_e32 v22, v25, v25
	v_fmac_f32_e32 v19, v18, v18
	v_mul_f32_e32 v18, v21, v21
	v_fmac_f32_e32 v30, v32, v32
	v_fmac_f32_e32 v26, v28, v28
	v_fmac_f32_e32 v22, v24, v24
	v_fmac_f32_e32 v18, v20, v20
	v_add_f32_e32 v30, v31, v30
	v_add_f32_e32 v26, v27, v26
	v_add_f32_e32 v22, v23, v22
	v_add_f32_e32 v18, v19, v18
	v_add_f32_e32 v26, v30, v26
	v_add_f32_e32 v18, v22, v18
	v_add_f32_e32 v18, v26, v18
	ds_bpermute_b32 v19, v122, v18
	s_waitcnt vmcnt(1)
	v_lshlrev_b32_e32 v20, 16, v70
	v_and_b32_e32 v21, 0xffff0000, v70
	v_lshlrev_b32_e32 v22, 16, v71
	v_and_b32_e32 v23, 0xffff0000, v71
	s_waitcnt lgkmcnt(0)
	v_add_f32_e32 v18, v18, v19
	ds_bpermute_b32 v19, v116, v18
	v_pk_add_f32 v[16:17], v[16:17], v[22:23]
	v_pk_add_f32 v[14:15], v[14:15], v[20:21]
	v_lshlrev_b32_e32 v20, 16, v72
	v_and_b32_e32 v21, 0xffff0000, v72
	v_lshlrev_b32_e32 v22, 16, v73
	v_and_b32_e32 v23, 0xffff0000, v73
	v_pk_add_f32 v[12:13], v[12:13], v[22:23]
	s_and_b64 vcc, exec, s[42:43]
	v_pk_add_f32 v[10:11], v[10:11], v[20:21]
	s_cbranch_vccnz .LBB0_756
	v_cvt_pk_bf16_f32 v20, v14, v15
	v_cvt_pk_bf16_f32 v21, v16, v17
	v_cvt_pk_bf16_f32 v22, v10, v11
	v_cvt_pk_bf16_f32 v23, v12, v13
	v_lshl_add_u64 v[94:95], v[94:95], 0, v[240:241]
	ds_bpermute_b32 v20, v242, v20
	ds_bpermute_b32 v21, v242, v21
	ds_bpermute_b32 v22, v242, v22
	ds_bpermute_b32 v23, v242, v23
	s_waitcnt lgkmcnt(0)
	global_store_dwordx4 v[94:95], v[20:23], off
.LBB0_756:
	s_waitcnt vmcnt(0)
	s_nop 0
	v_lshlrev_b32_e32 v20, 16, v66
	v_and_b32_e32 v21, 0xffff0000, v66
	v_lshlrev_b32_e32 v22, 16, v67
	v_and_b32_e32 v23, 0xffff0000, v67
	v_pk_add_f32 v[8:9], v[8:9], v[22:23]
	v_pk_add_f32 v[6:7], v[6:7], v[20:21]
	v_lshlrev_b32_e32 v20, 16, v68
	v_and_b32_e32 v21, 0xffff0000, v68
	v_lshlrev_b32_e32 v22, 16, v69
	v_and_b32_e32 v23, 0xffff0000, v69
	v_pk_add_f32 v[4:5], v[4:5], v[22:23]
	s_and_b64 vcc, exec, s[42:43]
	v_pk_add_f32 v[2:3], v[2:3], v[20:21]
	s_cbranch_vccnz .LBB0_758
	v_cvt_pk_bf16_f32 v20, v6, v7
	v_cvt_pk_bf16_f32 v21, v8, v9
	v_cvt_pk_bf16_f32 v22, v2, v3
	v_cvt_pk_bf16_f32 v23, v4, v5
	ds_bpermute_b32 v20, v242, v20
	ds_bpermute_b32 v21, v242, v21
	ds_bpermute_b32 v22, v242, v22
	ds_bpermute_b32 v23, v242, v23
	s_waitcnt lgkmcnt(0)
	global_store_dwordx4 v[94:95], v[20:23], off offset:256

.LBB0_1082:
	s_or_b64 exec, exec, s[38:39]
	s_lshl_b64 s[22:23], s[0:1], 2
	v_readlane_b32 s12, v255, 45
	s_barrier
	v_and_b32_e32 v229, 63, v204
	v_lshrrev_b32_e32 v230, 2, v229
	v_and_b32_e32 v226, 3, v229
	v_lshlrev_b32_e32 v228, 4, v226
	v_add_u32_e32 v228, v228, v230
	v_lshlrev_b32_e32 v228, 2, v228
	v_and_b32_e32 v227, 15, v229
	v_sub_u32_e32 v230, v230, v227
	v_lshlrev_b32_e32 v230, 12, v230
	v_bfe_u32 v227, v229, 4, 2
	v_sub_u32_e32 v226, v226, v227
	v_lshlrev_b32_e32 v226, 5, v226
	v_add_u32_e32 v226, v230, v226
	v_ashrrev_i32_e32 v227, 31, v226
	global_load_dwordx2 v[70:71], v[186:187], off sc1
	s_nop 0
	global_load_dwordx2 v[188:189], v[188:189], off sc1
	s_nop 0
	global_load_dwordx2 v[186:187], v[190:191], off sc1
	global_load_dwordx2 v[86:87], v[192:193], off sc1
	global_load_dwordx2 v[80:81], v[194:195], off sc1
	global_load_dwordx2 v[78:79], v[88:89], off sc1
	global_load_dwordx2 v[72:73], v[196:197], off sc1
	global_load_dwordx2 v[68:69], v[2:3], off sc1
	v_readlane_b32 s13, v255, 46
	s_add_u32 s1, s12, s22
	s_addc_u32 s19, s13, s23
	s_lshl_b32 s22, s21, 2
	v_lshlrev_b32_e32 v0, 3, v176
	s_add_u32 s22, s1, s22
	s_addc_u32 s23, s19, 0
	v_lshlrev_b32_e32 v6, 2, v0
	global_load_dwordx4 v[10:13], v6, s[22:23] offset:16
	global_load_dwordx4 v[14:17], v6, s[22:23]
	global_load_dwordx4 v[2:5], v6, s[22:23] offset:528
	s_nop 0
	global_load_dwordx4 v[6:9], v6, s[22:23] offset:512
	v_or_b32_e32 v0, s21, v0
	v_or_b32_e32 v88, s0, v0
	s_waitcnt vmcnt(11)
	v_ffbh_u32_e32 v0, v71
	v_min_u32_e32 v0, 32, v0
	v_lshlrev_b64 v[70:71], v0, v[70:71]
	v_min_u32_e32 v70, 1, v70
	v_or_b32_e32 v70, v71, v70
	v_cvt_f32_u32_e32 v70, v70
	v_sub_u32_e32 v0, 32, v0
	v_ashrrev_i32_e32 v89, 31, v88
	v_ldexp_f32 v0, v70, v0
	v_fmamk_f32 v0, v0, 0x30800000, v207
	v_cmp_gt_f32_e32 vcc, s16, v0
	v_mul_f32_e32 v70, 0x4b800000, v0
	s_nop 0
	v_cndmask_b32_e32 v0, v0, v70, vcc
	v_rsq_f32_e32 v0, v0
	s_nop 0
	v_mul_f32_e32 v70, 0x45800000, v0
	v_cndmask_b32_e32 v0, v0, v70, vcc
	v_lshlrev_b64 v[70:71], 12, v[160:161]
	v_pk_mul_f32 v[160:161], v[166:167], v[0:1] op_sel_hi:[1,0]
	v_pk_mul_f32 v[162:163], v[162:163], v[0:1] op_sel_hi:[1,0]
	v_lshl_add_u64 v[166:167], s[52:53], 0, v[70:71]
	v_lshlrev_b64 v[70:71], 2, v[88:89]
	s_waitcnt vmcnt(2)
	v_pk_mul_f32 v[162:163], v[16:17], v[162:163]
	v_pk_mul_f32 v[160:161], v[14:15], v[160:161]
	v_lshl_add_u64 v[88:89], v[166:167], 0, v[70:71]
	v_lshl_add_u64 v[88:89], v[88:89], 0, v[226:227]
	ds_bpermute_b32 v160, v228, v160
	ds_bpermute_b32 v161, v228, v161
	ds_bpermute_b32 v162, v228, v162
	ds_bpermute_b32 v163, v228, v163
	s_waitcnt lgkmcnt(0)
	global_store_dwordx4 v[88:89], v[160:163], off
	v_pk_mul_f32 v[128:129], v[128:129], v[0:1] op_sel_hi:[1,0]
	s_nop 0
	v_pk_mul_f32 v[160:161], v[164:165], v[0:1] op_sel_hi:[1,0]
	v_pk_mul_f32 v[162:163], v[12:13], v[128:129]
	v_pk_mul_f32 v[160:161], v[10:11], v[160:161]
	ds_bpermute_b32 v160, v228, v160
	ds_bpermute_b32 v161, v228, v161
	ds_bpermute_b32 v162, v228, v162
	ds_bpermute_b32 v163, v228, v163
	s_waitcnt lgkmcnt(0)
	global_store_dwordx4 v[88:89], v[160:163], off offset:16
	v_pk_mul_f32 v[128:129], v[170:171], v[0:1] op_sel_hi:[1,0]
	s_nop 0
	v_pk_mul_f32 v[160:161], v[168:169], v[0:1] op_sel_hi:[1,0]
	s_waitcnt vmcnt(2)
	v_pk_mul_f32 v[162:163], v[8:9], v[160:161]
	v_pk_mul_f32 v[160:161], v[6:7], v[128:129]
	ds_bpermute_b32 v160, v228, v160
	ds_bpermute_b32 v161, v228, v161
	ds_bpermute_b32 v162, v228, v162
	ds_bpermute_b32 v163, v228, v163
	s_waitcnt lgkmcnt(0)
	global_store_dwordx4 v[88:89], v[160:163], off offset:512
	v_pk_mul_f32 v[128:129], v[174:175], v[0:1] op_sel_hi:[1,0]
	s_nop 0
	v_pk_mul_f32 v[160:161], v[172:173], v[0:1] op_sel_hi:[1,0]
	v_ffbh_u32_e32 v0, v189
	v_pk_mul_f32 v[162:163], v[4:5], v[160:161]
	v_pk_mul_f32 v[160:161], v[2:3], v[128:129]
	v_min_u32_e32 v0, 32, v0
	ds_bpermute_b32 v160, v228, v160
	ds_bpermute_b32 v161, v228, v161
	ds_bpermute_b32 v162, v228, v162
	ds_bpermute_b32 v163, v228, v163
	s_waitcnt lgkmcnt(0)
	global_store_dwordx4 v[88:89], v[160:163], off offset:528
	v_lshlrev_b64 v[88:89], v0, v[188:189]
	v_min_u32_e32 v88, 1, v88
	v_or_b32_e32 v88, v89, v88
	v_cvt_f32_u32_e32 v88, v88
	v_sub_u32_e32 v0, 32, v0
	v_ldexp_f32 v0, v88, v0
	v_fmamk_f32 v0, v0, 0x30800000, v207
	v_cmp_gt_f32_e32 vcc, s16, v0
	v_mul_f32_e32 v88, 0x4b800000, v0
	s_nop 0
	v_cndmask_b32_e32 v0, v0, v88, vcc
	v_rsq_f32_e32 v0, v0
	s_nop 0
	v_mul_f32_e32 v88, 0x45800000, v0
	v_cndmask_b32_e32 v0, v0, v88, vcc
	v_lshlrev_b64 v[88:89], 12, v[158:159]
	v_pk_mul_f32 v[112:113], v[112:113], v[0:1] op_sel_hi:[1,0]
	v_lshl_add_u64 v[88:89], s[52:53], 0, v[88:89]
	v_pk_mul_f32 v[160:161], v[16:17], v[112:113]
	v_pk_mul_f32 v[112:113], v[124:125], v[0:1] op_sel_hi:[1,0]
	v_pk_mul_f32 v[114:115], v[114:115], v[0:1] op_sel_hi:[1,0]
	v_lshl_add_u64 v[88:89], v[88:89], 0, v[70:71]
	v_pk_mul_f32 v[114:115], v[12:13], v[114:115]
	v_pk_mul_f32 v[112:113], v[10:11], v[112:113]
	v_lshl_add_u64 v[88:89], v[88:89], 0, v[226:227]
	ds_bpermute_b32 v112, v228, v112
	ds_bpermute_b32 v113, v228, v113
	ds_bpermute_b32 v114, v228, v114
	ds_bpermute_b32 v115, v228, v115
	s_waitcnt lgkmcnt(0)
	global_store_dwordx4 v[88:89], v[112:115], off offset:16
	v_pk_mul_f32 v[116:117], v[116:117], v[0:1] op_sel_hi:[1,0]
	s_nop 0
	v_pk_mul_f32 v[112:113], v[150:151], v[0:1] op_sel_hi:[1,0]
	v_pk_mul_f32 v[114:115], v[146:147], v[0:1] op_sel_hi:[1,0]
	v_pk_mul_f32 v[112:113], v[6:7], v[112:113]
	v_pk_mul_f32 v[114:115], v[8:9], v[114:115]
	ds_bpermute_b32 v112, v228, v112
	ds_bpermute_b32 v113, v228, v113
	ds_bpermute_b32 v114, v228, v114
	ds_bpermute_b32 v115, v228, v115
	s_waitcnt lgkmcnt(0)
	global_store_dwordx4 v[88:89], v[112:115], off offset:512
	v_pk_mul_f32 v[158:159], v[14:15], v[116:117]
	ds_bpermute_b32 v158, v228, v158
	ds_bpermute_b32 v159, v228, v159
	ds_bpermute_b32 v160, v228, v160
	ds_bpermute_b32 v161, v228, v161
	s_waitcnt lgkmcnt(0)
	global_store_dwordx4 v[88:89], v[158:161], off
	v_pk_mul_f32 v[112:113], v[152:153], v[0:1] op_sel_hi:[1,0]
	v_pk_mul_f32 v[114:115], v[148:149], v[0:1] op_sel_hi:[1,0]
	v_ffbh_u32_e32 v0, v187
	v_pk_mul_f32 v[114:115], v[4:5], v[114:115]
	v_pk_mul_f32 v[112:113], v[2:3], v[112:113]
	v_min_u32_e32 v0, 32, v0
	ds_bpermute_b32 v112, v228, v112
	ds_bpermute_b32 v113, v228, v113
	ds_bpermute_b32 v114, v228, v114
	ds_bpermute_b32 v115, v228, v115
	s_waitcnt lgkmcnt(0)
	global_store_dwordx4 v[88:89], v[112:115], off offset:528
	v_lshlrev_b64 v[88:89], v0, v[186:187]
	v_min_u32_e32 v88, 1, v88
	v_or_b32_e32 v88, v89, v88
	v_cvt_f32_u32_e32 v88, v88
	v_sub_u32_e32 v0, 32, v0
	v_ldexp_f32 v0, v88, v0
	v_fmamk_f32 v0, v0, 0x30800000, v207
	v_cmp_gt_f32_e32 vcc, s16, v0
	v_mul_f32_e32 v88, 0x4b800000, v0
	s_nop 0
	v_cndmask_b32_e32 v0, v0, v88, vcc
	v_rsq_f32_e32 v0, v0
	s_nop 0
	v_mul_f32_e32 v88, 0x45800000, v0
	v_cndmask_b32_e32 v0, v0, v88, vcc
	v_lshlrev_b64 v[88:89], 12, v[156:157]
	v_pk_mul_f32 v[100:101], v[100:101], v[0:1] op_sel_hi:[1,0]
	v_pk_mul_f32 v[108:109], v[108:109], v[0:1] op_sel_hi:[1,0]
	v_pk_mul_f32 v[114:115], v[16:17], v[100:101]
	v_lshl_add_u64 v[88:89], s[52:53], 0, v[88:89]
	v_pk_mul_f32 v[100:101], v[120:121], v[0:1] op_sel_hi:[1,0]
	v_pk_mul_f32 v[106:107], v[106:107], v[0:1] op_sel_hi:[1,0]
	v_pk_mul_f32 v[112:113], v[14:15], v[108:109]
	v_lshl_add_u64 v[88:89], v[88:89], 0, v[70:71]
	v_pk_mul_f32 v[108:109], v[12:13], v[106:107]
	v_pk_mul_f32 v[106:107], v[10:11], v[100:101]
	v_lshl_add_u64 v[88:89], v[88:89], 0, v[226:227]
	ds_bpermute_b32 v106, v228, v106
	ds_bpermute_b32 v107, v228, v107
	ds_bpermute_b32 v108, v228, v108
	ds_bpermute_b32 v109, v228, v109
	s_waitcnt lgkmcnt(0)
	global_store_dwordx4 v[88:89], v[106:109], off offset:16
	v_pk_mul_f32 v[100:101], v[138:139], v[0:1] op_sel_hi:[1,0]
	ds_bpermute_b32 v112, v228, v112
	ds_bpermute_b32 v113, v228, v113
	ds_bpermute_b32 v114, v228, v114
	ds_bpermute_b32 v115, v228, v115
	s_waitcnt lgkmcnt(0)
	global_store_dwordx4 v[88:89], v[112:115], off
	v_pk_mul_f32 v[106:107], v[122:123], v[0:1] op_sel_hi:[1,0]
	s_nop 0
	v_pk_mul_f32 v[108:109], v[8:9], v[106:107]
	v_pk_mul_f32 v[106:107], v[6:7], v[100:101]
	ds_bpermute_b32 v106, v228, v106
	ds_bpermute_b32 v107, v228, v107
	ds_bpermute_b32 v108, v228, v108
	ds_bpermute_b32 v109, v228, v109
	s_waitcnt lgkmcnt(0)
	global_store_dwordx4 v[88:89], v[106:109], off offset:512
	v_pk_mul_f32 v[100:101], v[142:143], v[0:1] op_sel_hi:[1,0]
	s_nop 0
	v_pk_mul_f32 v[106:107], v[140:141], v[0:1] op_sel_hi:[1,0]
	v_ffbh_u32_e32 v0, v87
	v_min_u32_e32 v0, 32, v0
	v_lshlrev_b64 v[86:87], v0, v[86:87]
	v_min_u32_e32 v86, 1, v86
	v_or_b32_e32 v86, v87, v86
	v_cvt_f32_u32_e32 v86, v86
	v_sub_u32_e32 v0, 32, v0
	v_pk_mul_f32 v[108:109], v[4:5], v[106:107]
	v_pk_mul_f32 v[106:107], v[2:3], v[100:101]
	v_ldexp_f32 v0, v86, v0
	v_fmamk_f32 v0, v0, 0x30800000, v207
	v_cmp_gt_f32_e32 vcc, s16, v0
	v_mul_f32_e32 v86, 0x4b800000, v0
	v_lshlrev_b64 v[100:101], 12, v[154:155]
	v_cndmask_b32_e32 v0, v0, v86, vcc
	v_rsq_f32_e32 v0, v0
	ds_bpermute_b32 v106, v228, v106
	ds_bpermute_b32 v107, v228, v107
	ds_bpermute_b32 v108, v228, v108
	ds_bpermute_b32 v109, v228, v109
	s_waitcnt lgkmcnt(0)
	global_store_dwordx4 v[88:89], v[106:109], off offset:528
	v_mul_f32_e32 v86, 0x45800000, v0
	v_cndmask_b32_e32 v0, v0, v86, vcc
	v_pk_mul_f32 v[86:87], v[104:105], v[0:1] op_sel_hi:[1,0]
	v_pk_mul_f32 v[88:89], v[98:99], v[0:1] op_sel_hi:[1,0]
	v_lshl_add_u64 v[98:99], s[52:53], 0, v[100:101]
	v_pk_mul_f32 v[88:89], v[16:17], v[88:89]
	v_pk_mul_f32 v[86:87], v[14:15], v[86:87]
	v_lshl_add_u64 v[98:99], v[98:99], 0, v[70:71]
	v_lshl_add_u64 v[98:99], v[98:99], 0, v[226:227]
	ds_bpermute_b32 v86, v228, v86
	ds_bpermute_b32 v87, v228, v87
	ds_bpermute_b32 v88, v228, v88
	ds_bpermute_b32 v89, v228, v89
	s_waitcnt lgkmcnt(0)
	global_store_dwordx4 v[98:99], v[86:89], off
	s_nop 1
	v_pk_mul_f32 v[86:87], v[110:111], v[0:1] op_sel_hi:[1,0]
	v_pk_mul_f32 v[88:89], v[102:103], v[0:1] op_sel_hi:[1,0]
	v_pk_mul_f32 v[86:87], v[10:11], v[86:87]
	v_pk_mul_f32 v[88:89], v[12:13], v[88:89]
	ds_bpermute_b32 v86, v228, v86
	ds_bpermute_b32 v87, v228, v87
	ds_bpermute_b32 v88, v228, v88
	ds_bpermute_b32 v89, v228, v89
	s_waitcnt lgkmcnt(0)
	global_store_dwordx4 v[98:99], v[86:89], off offset:16
	s_nop 1
	v_pk_mul_f32 v[86:87], v[126:127], v[0:1] op_sel_hi:[1,0]
	v_pk_mul_f32 v[88:89], v[118:119], v[0:1] op_sel_hi:[1,0]
	v_pk_mul_f32 v[86:87], v[6:7], v[86:87]
	v_pk_mul_f32 v[88:89], v[8:9], v[88:89]
	ds_bpermute_b32 v86, v228, v86
	ds_bpermute_b32 v87, v228, v87
	ds_bpermute_b32 v88, v228, v88
	ds_bpermute_b32 v89, v228, v89
	s_waitcnt lgkmcnt(0)
	global_store_dwordx4 v[98:99], v[86:89], off offset:512
	s_nop 1
	v_pk_mul_f32 v[86:87], v[132:133], v[0:1] op_sel_hi:[1,0]
	v_pk_mul_f32 v[88:89], v[130:131], v[0:1] op_sel_hi:[1,0]
	v_ffbh_u32_e32 v0, v81
	v_min_u32_e32 v0, 32, v0
	v_lshlrev_b64 v[80:81], v0, v[80:81]
	v_min_u32_e32 v80, 1, v80
	v_or_b32_e32 v80, v81, v80
	v_cvt_f32_u32_e32 v80, v80
	v_sub_u32_e32 v0, 32, v0
	v_pk_mul_f32 v[88:89], v[4:5], v[88:89]
	v_pk_mul_f32 v[86:87], v[2:3], v[86:87]
	v_ldexp_f32 v0, v80, v0
	v_fmamk_f32 v0, v0, 0x30800000, v207
	v_cmp_gt_f32_e32 vcc, s16, v0
	v_mul_f32_e32 v80, 0x4b800000, v0
	ds_bpermute_b32 v86, v228, v86
	ds_bpermute_b32 v87, v228, v87
	ds_bpermute_b32 v88, v228, v88
	ds_bpermute_b32 v89, v228, v89
	s_waitcnt lgkmcnt(0)
	global_store_dwordx4 v[98:99], v[86:89], off offset:528
	v_cndmask_b32_e32 v0, v0, v80, vcc
	v_rsq_f32_e32 v0, v0
	s_nop 0
	v_mul_f32_e32 v80, 0x45800000, v0
	v_cndmask_b32_e32 v0, v0, v80, vcc
	v_lshlrev_b64 v[80:81], 12, v[96:97]
	v_lshl_add_u64 v[80:81], s[52:53], 0, v[80:81]
	v_pk_mul_f32 v[58:59], v[58:59], v[0:1] op_sel_hi:[1,0]
	v_pk_mul_f32 v[60:61], v[60:61], v[0:1] op_sel_hi:[1,0]
	v_lshl_add_u64 v[80:81], v[80:81], 0, v[70:71]
	v_pk_mul_f32 v[60:61], v[12:13], v[60:61]
	v_pk_mul_f32 v[58:59], v[10:11], v[58:59]
	v_lshl_add_u64 v[80:81], v[80:81], 0, v[226:227]
	ds_bpermute_b32 v58, v228, v58
	ds_bpermute_b32 v59, v228, v59
	ds_bpermute_b32 v60, v228, v60
	ds_bpermute_b32 v61, v228, v61
	s_waitcnt lgkmcnt(0)
	global_store_dwordx4 v[80:81], v[58:61], off offset:16
	v_pk_mul_f32 v[56:57], v[56:57], v[0:1] op_sel_hi:[1,0]
	v_pk_mul_f32 v[62:63], v[62:63], v[0:1] op_sel_hi:[1,0]
	v_pk_mul_f32 v[60:61], v[134:135], v[0:1] op_sel_hi:[1,0]
	v_pk_mul_f32 v[58:59], v[8:9], v[56:57]
	v_pk_mul_f32 v[56:57], v[6:7], v[60:61]
	v_pk_mul_f32 v[64:65], v[64:65], v[0:1] op_sel_hi:[1,0]
	ds_bpermute_b32 v56, v228, v56
	ds_bpermute_b32 v57, v228, v57
	ds_bpermute_b32 v58, v228, v58
	ds_bpermute_b32 v59, v228, v59
	s_waitcnt lgkmcnt(0)
	global_store_dwordx4 v[80:81], v[56:59], off offset:512
	v_pk_mul_f32 v[64:65], v[16:17], v[64:65]
	v_pk_mul_f32 v[62:63], v[14:15], v[62:63]
	v_pk_mul_f32 v[56:57], v[144:145], v[0:1] op_sel_hi:[1,0]
	v_pk_mul_f32 v[58:59], v[136:137], v[0:1] op_sel_hi:[1,0]
	v_ffbh_u32_e32 v0, v79
	v_pk_mul_f32 v[58:59], v[4:5], v[58:59]
	v_pk_mul_f32 v[56:57], v[2:3], v[56:57]
	v_min_u32_e32 v0, 32, v0
	ds_bpermute_b32 v56, v228, v56
	ds_bpermute_b32 v57, v228, v57
	ds_bpermute_b32 v58, v228, v58
	ds_bpermute_b32 v59, v228, v59
	s_waitcnt lgkmcnt(0)
	global_store_dwordx4 v[80:81], v[56:59], off offset:528
	ds_bpermute_b32 v62, v228, v62
	ds_bpermute_b32 v63, v228, v63
	ds_bpermute_b32 v64, v228, v64
	ds_bpermute_b32 v65, v228, v65
	s_waitcnt lgkmcnt(0)
	global_store_dwordx4 v[80:81], v[62:65], off
	s_nop 0
	v_lshlrev_b64 v[56:57], v0, v[78:79]
	v_min_u32_e32 v56, 1, v56
	v_or_b32_e32 v56, v57, v56
	v_cvt_f32_u32_e32 v56, v56
	v_sub_u32_e32 v0, 32, v0
	v_ldexp_f32 v0, v56, v0
	v_fmamk_f32 v0, v0, 0x30800000, v207
	v_cmp_gt_f32_e32 vcc, s16, v0
	v_mul_f32_e32 v56, 0x4b800000, v0
	s_nop 0
	v_cndmask_b32_e32 v0, v0, v56, vcc
	v_rsq_f32_e32 v0, v0
	s_nop 0
	v_mul_f32_e32 v56, 0x45800000, v0
	v_cndmask_b32_e32 v0, v0, v56, vcc
	v_lshlrev_b64 v[56:57], 12, v[94:95]
	v_lshl_add_u64 v[56:57], s[52:53], 0, v[56:57]
	v_pk_mul_f32 v[42:43], v[42:43], v[0:1] op_sel_hi:[1,0]
	v_pk_mul_f32 v[44:45], v[44:45], v[0:1] op_sel_hi:[1,0]
	v_lshl_add_u64 v[56:57], v[56:57], 0, v[70:71]
	v_pk_mul_f32 v[44:45], v[12:13], v[44:45]
	v_pk_mul_f32 v[42:43], v[10:11], v[42:43]
	v_lshl_add_u64 v[56:57], v[56:57], 0, v[226:227]
	ds_bpermute_b32 v42, v228, v42
	ds_bpermute_b32 v43, v228, v43
	ds_bpermute_b32 v44, v228, v44
	ds_bpermute_b32 v45, v228, v45
	s_waitcnt lgkmcnt(0)
	global_store_dwordx4 v[56:57], v[42:45], off offset:16
	v_pk_mul_f32 v[40:41], v[40:41], v[0:1] op_sel_hi:[1,0]
	v_pk_mul_f32 v[46:47], v[46:47], v[0:1] op_sel_hi:[1,0]
	v_pk_mul_f32 v[44:45], v[54:55], v[0:1] op_sel_hi:[1,0]
	v_pk_mul_f32 v[42:43], v[8:9], v[40:41]
	v_pk_mul_f32 v[40:41], v[6:7], v[44:45]
	v_pk_mul_f32 v[48:49], v[48:49], v[0:1] op_sel_hi:[1,0]
	ds_bpermute_b32 v40, v228, v40
	ds_bpermute_b32 v41, v228, v41
	ds_bpermute_b32 v42, v228, v42
	ds_bpermute_b32 v43, v228, v43
	s_waitcnt lgkmcnt(0)
	global_store_dwordx4 v[56:57], v[40:43], off offset:512
	v_pk_mul_f32 v[48:49], v[16:17], v[48:49]
	v_pk_mul_f32 v[46:47], v[14:15], v[46:47]
	v_pk_mul_f32 v[40:41], v[84:85], v[0:1] op_sel_hi:[1,0]
	v_pk_mul_f32 v[42:43], v[82:83], v[0:1] op_sel_hi:[1,0]
	v_ffbh_u32_e32 v0, v73
	v_pk_mul_f32 v[42:43], v[4:5], v[42:43]
	v_pk_mul_f32 v[40:41], v[2:3], v[40:41]
	v_min_u32_e32 v0, 32, v0
	ds_bpermute_b32 v40, v228, v40
	ds_bpermute_b32 v41, v228, v41
	ds_bpermute_b32 v42, v228, v42
	ds_bpermute_b32 v43, v228, v43
	s_waitcnt lgkmcnt(0)
	global_store_dwordx4 v[56:57], v[40:43], off offset:528
	ds_bpermute_b32 v46, v228, v46
	ds_bpermute_b32 v47, v228, v47
	ds_bpermute_b32 v48, v228, v48
	ds_bpermute_b32 v49, v228, v49
	s_waitcnt lgkmcnt(0)
	global_store_dwordx4 v[56:57], v[46:49], off
	s_nop 0
	v_lshlrev_b64 v[40:41], v0, v[72:73]
	v_min_u32_e32 v40, 1, v40
	v_or_b32_e32 v40, v41, v40
	v_cvt_f32_u32_e32 v40, v40
	v_sub_u32_e32 v0, 32, v0
	v_ldexp_f32 v0, v40, v0
	v_fmamk_f32 v0, v0, 0x30800000, v207
	v_cmp_gt_f32_e32 vcc, s16, v0
	v_mul_f32_e32 v40, 0x4b800000, v0
	s_nop 0
	v_cndmask_b32_e32 v0, v0, v40, vcc
	v_rsq_f32_e32 v0, v0
	s_nop 0
	v_mul_f32_e32 v40, 0x45800000, v0
	v_cndmask_b32_e32 v0, v0, v40, vcc
	v_lshlrev_b64 v[40:41], 12, v[92:93]
	v_pk_mul_f32 v[30:31], v[30:31], v[0:1] op_sel_hi:[1,0]
	v_pk_mul_f32 v[32:33], v[32:33], v[0:1] op_sel_hi:[1,0]
	v_lshl_add_u64 v[40:41], s[52:53], 0, v[40:41]
	v_pk_mul_f32 v[32:33], v[16:17], v[32:33]
	v_pk_mul_f32 v[30:31], v[14:15], v[30:31]
	v_lshl_add_u64 v[40:41], v[40:41], 0, v[70:71]
	v_lshl_add_u64 v[40:41], v[40:41], 0, v[226:227]
	ds_bpermute_b32 v30, v228, v30
	ds_bpermute_b32 v31, v228, v31
	ds_bpermute_b32 v32, v228, v32
	ds_bpermute_b32 v33, v228, v33
	s_waitcnt lgkmcnt(0)
	global_store_dwordx4 v[40:41], v[30:33], off
	v_pk_mul_f32 v[28:29], v[28:29], v[0:1] op_sel_hi:[1,0]
	s_nop 0
	v_pk_mul_f32 v[32:33], v[34:35], v[0:1] op_sel_hi:[1,0]
	v_pk_mul_f32 v[30:31], v[12:13], v[28:29]
	v_pk_mul_f32 v[28:29], v[10:11], v[32:33]
	ds_bpermute_b32 v28, v228, v28
	ds_bpermute_b32 v29, v228, v29
	ds_bpermute_b32 v30, v228, v30
	ds_bpermute_b32 v31, v228, v31
	s_waitcnt lgkmcnt(0)
	global_store_dwordx4 v[40:41], v[28:31], off offset:16
	s_nop 1
	v_pk_mul_f32 v[28:29], v[52:53], v[0:1] op_sel_hi:[1,0]
	v_pk_mul_f32 v[30:31], v[36:37], v[0:1] op_sel_hi:[1,0]
	v_pk_mul_f32 v[28:29], v[6:7], v[28:29]
	v_pk_mul_f32 v[30:31], v[8:9], v[30:31]
	ds_bpermute_b32 v28, v228, v28
	ds_bpermute_b32 v29, v228, v29
	ds_bpermute_b32 v30, v228, v30
	ds_bpermute_b32 v31, v228, v31
	s_waitcnt lgkmcnt(0)
	global_store_dwordx4 v[40:41], v[28:31], off offset:512
	s_nop 1
	v_pk_mul_f32 v[28:29], v[76:77], v[0:1] op_sel_hi:[1,0]
	v_pk_mul_f32 v[30:31], v[74:75], v[0:1] op_sel_hi:[1,0]
	v_ffbh_u32_e32 v0, v69
	v_pk_mul_f32 v[30:31], v[4:5], v[30:31]
	v_pk_mul_f32 v[28:29], v[2:3], v[28:29]
	v_min_u32_e32 v0, 32, v0
	ds_bpermute_b32 v28, v228, v28
	ds_bpermute_b32 v29, v228, v29
	ds_bpermute_b32 v30, v228, v30
	ds_bpermute_b32 v31, v228, v31
	s_waitcnt lgkmcnt(0)
	global_store_dwordx4 v[40:41], v[28:31], off offset:528
	s_nop 1
	v_lshlrev_b64 v[28:29], v0, v[68:69]
	v_min_u32_e32 v28, 1, v28
	v_or_b32_e32 v28, v29, v28
	v_cvt_f32_u32_e32 v28, v28
	v_sub_u32_e32 v0, 32, v0
	v_ldexp_f32 v0, v28, v0
	v_fmamk_f32 v0, v0, 0x30800000, v207
	v_cmp_gt_f32_e32 vcc, s16, v0
	v_mul_f32_e32 v28, 0x4b800000, v0
	s_nop 0
	v_cndmask_b32_e32 v0, v0, v28, vcc
	v_rsq_f32_e32 v0, v0
	s_nop 0
	v_mul_f32_e32 v28, 0x45800000, v0
	v_cndmask_b32_e32 v0, v0, v28, vcc
	v_lshlrev_b64 v[28:29], 12, v[90:91]
	v_pk_mul_f32 v[18:19], v[18:19], v[0:1] op_sel_hi:[1,0]
	v_pk_mul_f32 v[22:23], v[22:23], v[0:1] op_sel_hi:[1,0]
	v_pk_mul_f32 v[16:17], v[16:17], v[18:19]
	v_lshl_add_u64 v[18:19], s[52:53], 0, v[28:29]
	v_pk_mul_f32 v[14:15], v[14:15], v[22:23]
	v_lshl_add_u64 v[18:19], v[18:19], 0, v[70:71]
	v_lshl_add_u64 v[18:19], v[18:19], 0, v[226:227]
	ds_bpermute_b32 v14, v228, v14
	ds_bpermute_b32 v15, v228, v15
	ds_bpermute_b32 v16, v228, v16
	ds_bpermute_b32 v17, v228, v17
	s_waitcnt lgkmcnt(0)
	global_store_dwordx4 v[18:19], v[14:17], off
	s_nop 1
	v_pk_mul_f32 v[14:15], v[24:25], v[0:1] op_sel_hi:[1,0]
	v_pk_mul_f32 v[16:17], v[20:21], v[0:1] op_sel_hi:[1,0]
	v_pk_mul_f32 v[10:11], v[10:11], v[14:15]
	v_pk_mul_f32 v[12:13], v[12:13], v[16:17]
	ds_bpermute_b32 v10, v228, v10
	ds_bpermute_b32 v11, v228, v11
	ds_bpermute_b32 v12, v228, v12
	ds_bpermute_b32 v13, v228, v13
	s_waitcnt lgkmcnt(0)
	global_store_dwordx4 v[18:19], v[10:13], off offset:16
	s_nop 1
	v_pk_mul_f32 v[10:11], v[38:39], v[0:1] op_sel_hi:[1,0]
	v_pk_mul_f32 v[12:13], v[26:27], v[0:1] op_sel_hi:[1,0]
	v_pk_mul_f32 v[6:7], v[6:7], v[10:11]
	v_pk_mul_f32 v[8:9], v[8:9], v[12:13]
	ds_bpermute_b32 v6, v228, v6
	ds_bpermute_b32 v7, v228, v7
	ds_bpermute_b32 v8, v228, v8
	ds_bpermute_b32 v9, v228, v9
	s_waitcnt lgkmcnt(0)
	global_store_dwordx4 v[18:19], v[6:9], off offset:512
	s_nop 1
	v_pk_mul_f32 v[6:7], v[66:67], v[0:1] op_sel_hi:[1,0]
	v_pk_mul_f32 v[8:9], v[50:51], v[0:1] op_sel_hi:[1,0]
	v_pk_mul_f32 v[2:3], v[2:3], v[6:7]
	v_pk_mul_f32 v[4:5], v[4:5], v[8:9]
	ds_bpermute_b32 v2, v228, v2
	ds_bpermute_b32 v3, v228, v3
	ds_bpermute_b32 v4, v228, v4
	ds_bpermute_b32 v5, v228, v5
	s_waitcnt lgkmcnt(0)
	global_store_dwordx4 v[18:19], v[2:5], off offset:528
